# nt cache policy also on the final output stores (full 1 KB rows, never re-read), on top of nt for phase-0 input loads and the mixout residual loads
# baseline (speedup 1.0000x reference)
; __device__ __forceinline__ float bflo(uint32_t w) { return __uint_as_float(w << 16); }
; __device__ __forceinline__ float bfhi(uint32_t w) { return __uint_as_float(w & 0xffff0000u); }
; template <class G, class T> __device__ __forceinline__ G opaque_g(T* q) { asm volatile("" : "+v"(q)); return (G)q; }
; template <int MODE>
; __device__ void phase_ln(const Params& p, u16* smem) {
;     ...
;   for (int rb = (blockIdx.x * 4 + wid) * 2; rb < SEQ; rb += gridDim.x * 8) {
;     float v[2][32];
; #pragma unroll
;     for (int q = 0; q < 2; q++) {
;       const int r = rb + q;
;       if (MODE == 0) {
;         g_cv4 pr = opaque_g<g_cv4>(p.pre() + (long)r * DM + lane * 4);
; #pragma unroll
;         for (int i = 0; i < 8; i++) {
;           f32x4 a = pr[i * 64];
;           v[q][i * 4 + 0] = a[0]; v[q][i * 4 + 1] = a[1]; v[q][i * 4 + 2] = a[2]; v[q][i * 4 + 3] = a[3];
;         }
;       } else {
;         g_cu2 ph = opaque_g<g_cu2>(p.hb() + (long)r * DM + lane * 4);
;         g_cu2 py0 = opaque_g<g_cu2>(p.yslot() + (long)(2 * r) * DM + lane * 4);
;         g_cu2 py1 = opaque_g<g_cu2>(p.yslot() + (long)(2 * r + 1) * DM + lane * 4);
; #pragma unroll
;         for (int i = 0; i < 8; i++) {
;           u32x2 hw = ph[i * 64], y0 = py0[i * 64], y1 = py1[i * 64];
;           v[q][i * 4 + 0] = DN_ALPHA * bflo(hw[0]) + (bflo(y0[0]) + bflo(y1[0]));
;           v[q][i * 4 + 1] = DN_ALPHA * bfhi(hw[0]) + (bfhi(y0[0]) + bfhi(y1[0]));
;           v[q][i * 4 + 2] = DN_ALPHA * bflo(hw[1]) + (bflo(y0[1]) + bflo(y1[1]));
;           v[q][i * 4 + 3] = DN_ALPHA * bfhi(hw[1]) + (bfhi(y0[1]) + bfhi(y1[1]));
;         }
;       }
.LBB0_1054:
	v_cmp_lt_i32_e32 vcc, v102, v101
	v_ashrrev_i32_e32 v133, 31, v132
	v_add_u32_e32 v0, -3, v18
	v_cndmask_b32_e32 v26, v100, v102, vcc
	v_cmp_lt_i32_e32 vcc, v103, v101
	v_add_u32_e32 v2, -2, v18
	v_lshlrev_b64 v[6:7], 12, v[132:133]
	v_cndmask_b32_e32 v27, v100, v103, vcc
	v_ashrrev_i32_e32 v1, 31, v0
	v_ashrrev_i32_e32 v3, 31, v2
	v_lshlrev_b32_e32 v113, 2, v26
	v_lshlrev_b32_e32 v112, 2, v27
	v_lshlrev_b64 v[26:27], 13, v[132:133]
	v_lshl_add_u64 v[6:7], v[12:13], 0, v[6:7]
	v_lshlrev_b64 v[0:1], 12, v[0:1]
	v_lshlrev_b64 v[2:3], 12, v[2:3]
	v_lshl_add_u64 v[58:59], v[16:17], 0, v[26:27]
	v_mov_b64_e32 v[26:27], v[6:7]
	v_lshl_add_u64 v[0:1], v[14:15], 0, v[0:1]
	v_lshl_add_u64 v[2:3], v[14:15], 0, v[2:3]
	global_load_dwordx2 v[84:85], v[26:27], off offset:3584
	global_load_dwordx2 v[86:87], v[0:1], off offset:3584
	global_load_dwordx2 v[88:89], v[2:3], off offset:3584
	global_load_dwordx2 v[90:91], v[26:27], off
	global_load_dwordx2 v[92:93], v[0:1], off
	global_load_dwordx2 v[94:95], v[2:3], off
	global_load_dwordx2 v[96:97], v[26:27], off offset:512
	global_load_dwordx2 v[98:99], v[0:1], off offset:512
	global_load_dwordx2 v[114:115], v[2:3], off offset:512
	global_load_dwordx2 v[116:117], v[26:27], off offset:2048
	global_load_dwordx2 v[118:119], v[26:27], off offset:2560
	global_load_dwordx2 v[72:73], v[26:27], off offset:3072
	global_load_dwordx2 v[120:121], v[26:27], off offset:1024
	global_load_dwordx2 v[122:123], v[0:1], off offset:1024
	global_load_dwordx2 v[124:125], v[0:1], off offset:2048
	global_load_dwordx2 v[126:127], v[0:1], off offset:2560
	global_load_dwordx2 v[74:75], v[0:1], off offset:3072
	global_load_dwordx2 v[128:129], v[2:3], off offset:1024
	global_load_dwordx2 v[130:131], v[2:3], off offset:2048
	global_load_dwordx2 v[134:135], v[2:3], off offset:2560
	global_load_dwordx2 v[82:83], v[2:3], off offset:3072
	global_load_dwordx2 v[136:137], v[26:27], off offset:1536
	global_load_dwordx2 v[138:139], v[0:1], off offset:1536
	global_load_dwordx2 v[140:141], v[2:3], off offset:1536
	v_cmp_lt_i32_e32 vcc, v104, v101
	v_ashrrev_i32_e32 v19, 31, v18
	v_add_u32_e32 v44, 1, v132
	v_cndmask_b32_e32 v28, v100, v104, vcc
	v_lshlrev_b32_e32 v111, 2, v28
	v_cmp_lt_i32_e32 vcc, v105, v101
	v_lshlrev_b64 v[24:25], 12, v[18:19]
	v_add_u32_e32 v4, -1, v18
	v_cndmask_b32_e32 v29, v100, v105, vcc
	v_lshlrev_b32_e32 v110, 2, v29
	v_cmp_lt_i32_e32 vcc, v106, v101
	v_ashrrev_i32_e32 v45, 31, v44
	v_ashrrev_i32_e32 v5, 31, v4
	v_cndmask_b32_e32 v30, v100, v106, vcc
	v_lshlrev_b32_e32 v109, 2, v30
	v_cmp_lt_i32_e32 vcc, v107, v101
	v_lshlrev_b64 v[28:29], 12, v[44:45]
	v_lshlrev_b64 v[4:5], 12, v[4:5]
	v_cndmask_b32_e32 v31, v100, v107, vcc
	v_lshlrev_b32_e32 v19, 2, v31
	v_lshl_add_u64 v[80:81], v[14:15], 0, v[24:25]
	v_lshl_add_u64 v[24:25], v[12:13], 0, v[28:29]
	v_lshl_add_u64 v[4:5], v[14:15], 0, v[4:5]
	v_mov_b64_e32 v[28:29], v[24:25]
	v_mov_b64_e32 v[20:21], v[8:9]
	v_mov_b64_e32 v[22:23], v[10:11]
	global_load_dwordx2 v[66:67], v[28:29], off
	global_load_dwordx2 v[60:61], v[28:29], off offset:512
	global_load_dwordx2 v[52:53], v[28:29], off offset:1024
	global_load_dwordx2 v[46:47], v[28:29], off offset:1536
	global_load_dwordx2 v[68:69], v[4:5], off
	global_load_dwordx2 v[62:63], v[4:5], off offset:512
	global_load_dwordx2 v[54:55], v[4:5], off offset:1024
	global_load_dwordx2 v[48:49], v[4:5], off offset:1536
	global_load_dwordx2 v[70:71], v[80:81], off
	global_load_dwordx2 v[64:65], v[80:81], off offset:512
	global_load_dwordx2 v[56:57], v[80:81], off offset:1024
	global_load_dwordx2 v[50:51], v[80:81], off offset:1536
	global_load_dwordx2 v[38:39], v[28:29], off offset:2048
	global_load_dwordx2 v[32:33], v[28:29], off offset:2560
	global_load_dwordx2 v[26:27], v[28:29], off offset:3072
	global_load_dwordx2 v[76:77], v[28:29], off offset:3584
	global_load_dwordx2 v[40:41], v[4:5], off offset:2048
	global_load_dwordx2 v[34:35], v[4:5], off offset:2560
	s_nop 0
	global_load_dwordx2 v[28:29], v[4:5], off offset:3072
	global_load_dwordx2 v[78:79], v[4:5], off offset:3584
	global_load_dwordx2 v[42:43], v[80:81], off offset:2048
	global_load_dwordx2 v[36:37], v[80:81], off offset:2560
	global_load_dwordx2 v[30:31], v[80:81], off offset:3072
	s_nop 0
	global_load_dwordx2 v[80:81], v[80:81], off offset:3584
	global_load_dwordx4 v[0:3], v[20:21], off
	global_load_dwordx4 v[4:7], v[22:23], off
	v_add_u32_e32 v132, s3, v132
	v_add_u32_e32 v18, s4, v18
	s_waitcnt vmcnt(49)
	v_and_b32_e32 v142, 0xffff0000, v84
	s_waitcnt vmcnt(48)
	v_and_b32_e32 v144, 0xffff0000, v86
	v_lshlrev_b32_e32 v145, 16, v86
	s_waitcnt vmcnt(47)
	v_and_b32_e32 v146, 0xffff0000, v88
	v_lshlrev_b32_e32 v147, 16, v88
	v_and_b32_e32 v86, 0xffff0000, v87
	v_lshlrev_b32_e32 v87, 16, v87
	v_and_b32_e32 v88, 0xffff0000, v89
	v_lshlrev_b32_e32 v89, 16, v89
	s_waitcnt vmcnt(45)
	v_lshlrev_b32_e32 v150, 16, v92
	v_and_b32_e32 v151, 0xffff0000, v92
	s_waitcnt vmcnt(44)
	v_lshlrev_b32_e32 v152, 16, v94
	v_and_b32_e32 v153, 0xffff0000, v94
	v_lshlrev_b32_e32 v143, 16, v84
	v_and_b32_e32 v84, 0xffff0000, v85
	v_lshlrev_b32_e32 v85, 16, v85
	v_lshlrev_b32_e32 v148, 16, v90
	v_and_b32_e32 v149, 0xffff0000, v90
	s_waitcnt vmcnt(33)
	v_lshlrev_b32_e32 v186, 16, v74
	v_and_b32_e32 v187, 0xffff0000, v74
	s_waitcnt vmcnt(29)
; __device__ __forceinline__ float bflo(uint32_t w) { return __uint_as_float(w << 16); }
; __device__ __forceinline__ float bfhi(uint32_t w) { return __uint_as_float(w & 0xffff0000u); }
; __device__ __forceinline__ void ln_stats(const float (&v)[32], float& mean, float& rstd) {
;   float s = 0.f;
; #pragma unroll
;   for (int i = 0; i < 32; i++) s += v[i];
;   mean = wave_sum(s) * (1.f / DM);
; template <int MODE>
; __device__ void phase_ln(const Params& p, u16* smem) {
;     ...
;         for (int i = 0; i < 8; i++) {
;           u32x2 hw = ph[i * 64], y0 = py0[i * 64], y1 = py1[i * 64];
;           v[q][i * 4 + 0] = DN_ALPHA * bflo(hw[0]) + (bflo(y0[0]) + bflo(y1[0]));
;           v[q][i * 4 + 1] = DN_ALPHA * bfhi(hw[0]) + (bfhi(y0[0]) + bfhi(y1[0]));
;           v[q][i * 4 + 2] = DN_ALPHA * bflo(hw[1]) + (bflo(y0[1]) + bflo(y1[1]));
;           v[q][i * 4 + 3] = DN_ALPHA * bfhi(hw[1]) + (bfhi(y0[1]) + bfhi(y1[1]));
;         }
	v_lshlrev_b32_e32 v188, 16, v82
	v_and_b32_e32 v189, 0xffff0000, v82
	v_lshlrev_b32_e32 v74, 16, v75
	v_and_b32_e32 v75, 0xffff0000, v75
	v_lshlrev_b32_e32 v82, 16, v83
	v_and_b32_e32 v83, 0xffff0000, v83
	v_pk_add_f32 v[144:145], v[144:145], v[146:147]
	v_pk_add_f32 v[86:87], v[86:87], v[88:89]
	v_pk_add_f32 v[88:89], v[150:151], v[152:153]
	v_lshlrev_b32_e32 v92, 16, v93
	v_and_b32_e32 v93, 0xffff0000, v93
	v_lshlrev_b32_e32 v94, 16, v95
	v_and_b32_e32 v95, 0xffff0000, v95
	v_lshlrev_b32_e32 v184, 16, v72
	v_and_b32_e32 v185, 0xffff0000, v72
	v_lshlrev_b32_e32 v72, 16, v73
	v_and_b32_e32 v73, 0xffff0000, v73
	v_pk_add_f32 v[74:75], v[74:75], v[82:83]
	v_pk_fma_f32 v[82:83], v[142:143], s[2:3], v[144:145] op_sel_hi:[1,0,1]
	v_pk_fma_f32 v[142:143], v[84:85], s[2:3], v[86:87] op_sel_hi:[1,0,1]
	v_pk_fma_f32 v[84:85], v[148:149], s[2:3], v[88:89] op_sel_hi:[1,0,1]
	v_lshlrev_b32_e32 v90, 16, v91
	v_and_b32_e32 v91, 0xffff0000, v91
	v_pk_add_f32 v[92:93], v[92:93], v[94:95]
	v_pk_fma_f32 v[72:73], v[72:73], s[2:3], v[74:75] op_sel_hi:[1,0,1]
	v_add_f32_e32 v74, 0, v84
	v_lshlrev_b32_e32 v156, 16, v98
	v_and_b32_e32 v157, 0xffff0000, v98
	v_lshlrev_b32_e32 v158, 16, v114
	v_and_b32_e32 v159, 0xffff0000, v114
	v_pk_fma_f32 v[86:87], v[90:91], s[2:3], v[92:93] op_sel_hi:[1,0,1]
	v_add_f32_e32 v74, v85, v74
	v_lshlrev_b32_e32 v154, 16, v96
	v_and_b32_e32 v155, 0xffff0000, v96
	v_pk_add_f32 v[94:95], v[156:157], v[158:159]
	v_add_f32_e32 v74, v86, v74
	v_lshlrev_b32_e32 v98, 16, v99
	v_and_b32_e32 v99, 0xffff0000, v99
	v_lshlrev_b32_e32 v114, 16, v115
	v_and_b32_e32 v115, 0xffff0000, v115
	v_pk_fma_f32 v[88:89], v[154:155], s[2:3], v[94:95] op_sel_hi:[1,0,1]
	v_add_f32_e32 v74, v87, v74
	v_lshlrev_b32_e32 v96, 16, v97
	v_and_b32_e32 v97, 0xffff0000, v97
	v_pk_add_f32 v[98:99], v[98:99], v[114:115]
	v_add_f32_e32 v74, v88, v74
	v_lshlrev_b32_e32 v162, 16, v122
	v_and_b32_e32 v163, 0xffff0000, v122
	v_lshlrev_b32_e32 v164, 16, v128
	v_and_b32_e32 v165, 0xffff0000, v128
	v_pk_fma_f32 v[90:91], v[96:97], s[2:3], v[98:99] op_sel_hi:[1,0,1]
	v_add_f32_e32 v74, v89, v74
	v_lshlrev_b32_e32 v160, 16, v120
	v_and_b32_e32 v161, 0xffff0000, v120
	v_pk_add_f32 v[114:115], v[162:163], v[164:165]
	v_add_f32_e32 v74, v90, v74
	v_lshlrev_b32_e32 v122, 16, v123
	v_and_b32_e32 v123, 0xffff0000, v123
	v_lshlrev_b32_e32 v128, 16, v129
	v_and_b32_e32 v129, 0xffff0000, v129
	v_pk_fma_f32 v[92:93], v[160:161], s[2:3], v[114:115] op_sel_hi:[1,0,1]
	v_add_f32_e32 v74, v91, v74
	v_lshlrev_b32_e32 v120, 16, v121
	v_and_b32_e32 v121, 0xffff0000, v121
	v_pk_add_f32 v[122:123], v[122:123], v[128:129]
	v_add_f32_e32 v74, v92, v74
	s_waitcnt vmcnt(27)
	v_lshlrev_b32_e32 v168, 16, v138
	v_and_b32_e32 v169, 0xffff0000, v138
	s_waitcnt vmcnt(26)
	v_lshlrev_b32_e32 v170, 16, v140
	v_and_b32_e32 v171, 0xffff0000, v140
	v_pk_fma_f32 v[94:95], v[120:121], s[2:3], v[122:123] op_sel_hi:[1,0,1]
	v_add_f32_e32 v74, v93, v74
	v_lshlrev_b32_e32 v166, 16, v136
	v_and_b32_e32 v167, 0xffff0000, v136
	v_pk_add_f32 v[128:129], v[168:169], v[170:171]
	v_add_f32_e32 v74, v94, v74
	v_lshlrev_b32_e32 v138, 16, v139
	v_and_b32_e32 v139, 0xffff0000, v139
	v_lshlrev_b32_e32 v140, 16, v141
	v_and_b32_e32 v141, 0xffff0000, v141
	v_pk_fma_f32 v[96:97], v[166:167], s[2:3], v[128:129] op_sel_hi:[1,0,1]
	v_add_f32_e32 v74, v95, v74
	v_lshlrev_b32_e32 v136, 16, v137
	v_and_b32_e32 v137, 0xffff0000, v137
	v_pk_add_f32 v[138:139], v[138:139], v[140:141]
	v_add_f32_e32 v74, v96, v74
	v_lshlrev_b32_e32 v174, 16, v124
	v_and_b32_e32 v175, 0xffff0000, v124
	v_lshlrev_b32_e32 v176, 16, v130
	v_and_b32_e32 v177, 0xffff0000, v130
	v_pk_fma_f32 v[98:99], v[136:137], s[2:3], v[138:139] op_sel_hi:[1,0,1]
	v_add_f32_e32 v74, v97, v74
	v_lshlrev_b32_e32 v172, 16, v116
	v_and_b32_e32 v173, 0xffff0000, v116
	v_pk_add_f32 v[140:141], v[174:175], v[176:177]
	v_add_f32_e32 v74, v98, v74
	v_lshlrev_b32_e32 v124, 16, v125
	v_and_b32_e32 v125, 0xffff0000, v125
	v_lshlrev_b32_e32 v130, 16, v131
	v_and_b32_e32 v131, 0xffff0000, v131
	v_pk_fma_f32 v[114:115], v[172:173], s[2:3], v[140:141] op_sel_hi:[1,0,1]
	v_add_f32_e32 v74, v99, v74
	v_lshlrev_b32_e32 v116, 16, v117
	v_and_b32_e32 v117, 0xffff0000, v117
	v_pk_add_f32 v[124:125], v[124:125], v[130:131]
	v_add_f32_e32 v74, v114, v74
	v_lshlrev_b32_e32 v180, 16, v126
	v_and_b32_e32 v181, 0xffff0000, v126
	v_lshlrev_b32_e32 v182, 16, v134
	v_and_b32_e32 v183, 0xffff0000, v134
	v_pk_fma_f32 v[116:117], v[116:117], s[2:3], v[124:125] op_sel_hi:[1,0,1]
	v_add_f32_e32 v74, v115, v74
	v_lshlrev_b32_e32 v178, 16, v118
	v_and_b32_e32 v179, 0xffff0000, v118
	v_pk_add_f32 v[130:131], v[180:181], v[182:183]
	v_add_f32_e32 v74, v116, v74
	v_lshlrev_b32_e32 v126, 16, v127
	v_and_b32_e32 v127, 0xffff0000, v127
	v_lshlrev_b32_e32 v134, 16, v135
	v_and_b32_e32 v135, 0xffff0000, v135
	v_pk_fma_f32 v[120:121], v[178:179], s[2:3], v[130:131] op_sel_hi:[1,0,1]
	v_add_f32_e32 v74, v117, v74
	v_lshlrev_b32_e32 v118, 16, v119
	v_and_b32_e32 v119, 0xffff0000, v119
	v_pk_add_f32 v[126:127], v[126:127], v[134:135]
	v_add_f32_e32 v74, v120, v74
	v_pk_fma_f32 v[118:119], v[118:119], s[2:3], v[126:127] op_sel_hi:[1,0,1]
	v_add_f32_e32 v74, v121, v74
	v_pk_add_f32 v[134:135], v[186:187], v[188:189]
	v_add_f32_e32 v74, v118, v74
	v_pk_fma_f32 v[122:123], v[184:185], s[2:3], v[134:135] op_sel_hi:[1,0,1]
	v_add_f32_e32 v74, v119, v74
	v_add_f32_e32 v74, v122, v74
	v_add_f32_e32 v74, v123, v74
	v_add_f32_e32 v74, v72, v74
	v_add_f32_e32 v74, v73, v74
	v_add_f32_e32 v74, v83, v74
	v_add_f32_e32 v74, v82, v74
	v_add_f32_e32 v74, v143, v74
	v_add_f32_e32 v74, v142, v74
	ds_bpermute_b32 v75, v113, v74
	s_waitcnt vmcnt(9)
; __device__ __forceinline__ float wave_sum(float v) {
; #pragma unroll
;   for (int o = 32; o; o >>= 1) v += __shfl_xor(v, o);
;   return v;
; __device__ __forceinline__ void ln_stats(const float (&v)[32], float& mean, float& rstd) {
;   float s = 0.f;
; #pragma unroll
;   for (int i = 0; i < 32; i++) s += v[i];
;   mean = wave_sum(s) * (1.f / DM);
;   float q = 0.f;
; #pragma unroll
;   for (int i = 0; i < 32; i++) { float d = v[i] - mean; q += d * d; }
;   rstd = rsqrtf(wave_sum(q) * (1.f / DM) + 1e-5f);
; }
	v_lshlrev_b32_e32 v158, 16, v41
	v_and_b32_e32 v159, 0xffff0000, v41
	s_waitcnt vmcnt(8)
	v_lshlrev_b32_e32 v162, 16, v34
	v_and_b32_e32 v163, 0xffff0000, v34
	s_waitcnt lgkmcnt(0)
	v_add_f32_e32 v74, v74, v75
	ds_bpermute_b32 v75, v112, v74
	v_lshlrev_b32_e32 v160, 16, v32
	v_and_b32_e32 v161, 0xffff0000, v32
	v_lshlrev_b32_e32 v34, 16, v35
	v_and_b32_e32 v35, 0xffff0000, v35
	s_waitcnt lgkmcnt(0)
	v_add_f32_e32 v74, v74, v75
	ds_bpermute_b32 v75, v111, v74
	v_lshlrev_b32_e32 v32, 16, v33
	v_and_b32_e32 v33, 0xffff0000, v33
	s_waitcnt lgkmcnt(0)
	v_add_f32_e32 v74, v74, v75
	ds_bpermute_b32 v75, v110, v74
	s_waitcnt lgkmcnt(0)
	v_add_f32_e32 v74, v74, v75
	ds_bpermute_b32 v75, v109, v74
	s_waitcnt lgkmcnt(0)
	v_add_f32_e32 v74, v74, v75
	ds_bpermute_b32 v75, v19, v74
	s_waitcnt lgkmcnt(0)
	v_add_f32_e32 v74, v74, v75
	v_mul_f32_e32 v74, 0x3a000000, v74
	v_pk_add_f32 v[124:125], v[84:85], v[74:75] op_sel_hi:[1,0] neg_lo:[0,1] neg_hi:[0,1]
	v_pk_add_f32 v[126:127], v[86:87], v[74:75] op_sel_hi:[1,0] neg_lo:[0,1] neg_hi:[0,1]
	v_pk_add_f32 v[86:87], v[72:73], v[74:75] op_sel_hi:[1,0] neg_lo:[0,1] neg_hi:[0,1]
	v_pk_add_f32 v[72:73], v[82:83], v[74:75] op_sel_hi:[1,0] neg_lo:[0,1] neg_hi:[0,1]
	v_pk_mul_f32 v[82:83], v[124:125], v[124:125]
	v_pk_add_f32 v[134:135], v[92:93], v[74:75] op_sel_hi:[1,0] neg_lo:[0,1] neg_hi:[0,1]
	v_pk_add_f32 v[92:93], v[114:115], v[74:75] op_sel_hi:[1,0] neg_lo:[0,1] neg_hi:[0,1]
	v_pk_mul_f32 v[114:115], v[126:127], v[126:127]
	v_add_f32_e32 v82, v82, v83
	v_pk_add_f32 v[128:129], v[88:89], v[74:75] op_sel_hi:[1,0] neg_lo:[0,1] neg_hi:[0,1]
	v_add_f32_e32 v82, v114, v82
	v_pk_add_f32 v[136:137], v[94:95], v[74:75] op_sel_hi:[1,0] neg_lo:[0,1] neg_hi:[0,1]
	v_pk_add_f32 v[94:95], v[116:117], v[74:75] op_sel_hi:[1,0] neg_lo:[0,1] neg_hi:[0,1]
	v_pk_mul_f32 v[116:117], v[128:129], v[128:129]
	v_add_f32_e32 v82, v115, v82
	v_pk_add_f32 v[130:131], v[90:91], v[74:75] op_sel_hi:[1,0] neg_lo:[0,1] neg_hi:[0,1]
	v_add_f32_e32 v82, v116, v82
	v_pk_add_f32 v[90:91], v[118:119], v[74:75] op_sel_hi:[1,0] neg_lo:[0,1] neg_hi:[0,1]
	v_pk_mul_f32 v[118:119], v[130:131], v[130:131]
	v_add_f32_e32 v82, v117, v82
	v_add_f32_e32 v82, v118, v82
	v_pk_add_f32 v[88:89], v[120:121], v[74:75] op_sel_hi:[1,0] neg_lo:[0,1] neg_hi:[0,1]
	v_pk_mul_f32 v[120:121], v[134:135], v[134:135]
	v_add_f32_e32 v82, v119, v82
	v_add_f32_e32 v82, v120, v82
	v_pk_add_f32 v[84:85], v[122:123], v[74:75] op_sel_hi:[1,0] neg_lo:[0,1] neg_hi:[0,1]
	v_pk_mul_f32 v[122:123], v[136:137], v[136:137]
	v_add_f32_e32 v82, v121, v82
	v_pk_add_f32 v[96:97], v[96:97], v[74:75] op_sel_hi:[1,0] neg_lo:[0,1] neg_hi:[0,1]
	v_add_f32_e32 v82, v122, v82
	v_pk_mul_f32 v[138:139], v[96:97], v[96:97]
	v_add_f32_e32 v82, v123, v82
	v_pk_add_f32 v[98:99], v[98:99], v[74:75] op_sel_hi:[1,0] neg_lo:[0,1] neg_hi:[0,1]
	v_add_f32_e32 v82, v138, v82
	v_pk_mul_f32 v[140:141], v[98:99], v[98:99]
	v_add_f32_e32 v82, v139, v82
	v_add_f32_e32 v82, v140, v82
	v_pk_add_f32 v[74:75], v[142:143], v[74:75] op_sel_hi:[1,0] neg_lo:[0,1] neg_hi:[0,1]
	v_pk_mul_f32 v[142:143], v[92:93], v[92:93]
	v_add_f32_e32 v82, v141, v82
	v_add_f32_e32 v82, v142, v82
	v_pk_mul_f32 v[144:145], v[94:95], v[94:95]
	v_add_f32_e32 v82, v143, v82
	v_add_f32_e32 v82, v144, v82
	v_pk_mul_f32 v[146:147], v[88:89], v[88:89]
	v_add_f32_e32 v82, v145, v82
	v_add_f32_e32 v82, v146, v82
	v_pk_mul_f32 v[148:149], v[90:91], v[90:91]
	v_add_f32_e32 v82, v147, v82
	v_add_f32_e32 v82, v148, v82
	v_pk_mul_f32 v[150:151], v[84:85], v[84:85]
	v_add_f32_e32 v82, v149, v82
	v_add_f32_e32 v82, v150, v82
	v_pk_mul_f32 v[152:153], v[86:87], v[86:87]
	v_add_f32_e32 v82, v151, v82
	v_add_f32_e32 v82, v152, v82
	v_pk_mul_f32 v[154:155], v[72:73], v[72:73]
	v_add_f32_e32 v82, v153, v82
	v_add_f32_e32 v82, v155, v82
	v_pk_mul_f32 v[156:157], v[74:75], v[74:75]
	v_add_f32_e32 v82, v154, v82
	v_add_f32_e32 v82, v157, v82
	v_add_f32_e32 v82, v156, v82
	ds_bpermute_b32 v83, v113, v82
	v_lshlrev_b32_e32 v138, 16, v67
	v_and_b32_e32 v139, 0xffff0000, v67
	v_lshlrev_b32_e32 v140, 16, v69
	v_and_b32_e32 v141, 0xffff0000, v69
	s_waitcnt lgkmcnt(0)
	v_add_f32_e32 v82, v82, v83
	ds_bpermute_b32 v83, v112, v82
	s_waitcnt vmcnt(6)
	v_and_b32_e32 v122, 0xffff0000, v78
	v_lshlrev_b32_e32 v123, 16, v78
	v_lshlrev_b32_e32 v150, 16, v38
	v_and_b32_e32 v151, 0xffff0000, v38
	s_waitcnt lgkmcnt(0)
	v_add_f32_e32 v82, v82, v83
	ds_bpermute_b32 v83, v111, v82
	v_lshlrev_b32_e32 v152, 16, v40
	v_and_b32_e32 v153, 0xffff0000, v40
	v_lshlrev_b32_e32 v156, 16, v39
	v_and_b32_e32 v157, 0xffff0000, v39
	s_waitcnt lgkmcnt(0)
	v_add_f32_e32 v82, v82, v83
	ds_bpermute_b32 v83, v110, v82
	v_lshlrev_b32_e32 v146, 16, v47
	v_and_b32_e32 v147, 0xffff0000, v47
	v_lshlrev_b32_e32 v148, 16, v49
	v_and_b32_e32 v149, 0xffff0000, v49
	s_waitcnt lgkmcnt(0)
	v_add_f32_e32 v82, v82, v83
	ds_bpermute_b32 v83, v109, v82
	v_lshlrev_b32_e32 v142, 16, v60
	v_and_b32_e32 v143, 0xffff0000, v60
	v_lshlrev_b32_e32 v60, 16, v61
	v_and_b32_e32 v61, 0xffff0000, v61
	s_waitcnt lgkmcnt(0)
	v_add_f32_e32 v82, v82, v83
	ds_bpermute_b32 v83, v19, v82
	v_lshlrev_b32_e32 v144, 16, v50
	v_and_b32_e32 v145, 0xffff0000, v50
	v_lshlrev_b32_e32 v50, 16, v51
	v_and_b32_e32 v51, 0xffff0000, v51
	s_waitcnt lgkmcnt(0)
	v_add_f32_e32 v82, v82, v83
	v_fmamk_f32 v82, v82, 0x3a000000, v108
	v_mul_f32_e32 v83, 0x4b800000, v82
	v_cmp_gt_f32_e32 vcc, s5, v82
	v_pk_add_f32 v[50:51], v[148:149], v[50:51]
	s_waitcnt vmcnt(5)
; template <class G, class T> __device__ __forceinline__ G opaque_g(T* q) { asm volatile("" : "+v"(q)); return (G)q; }
; __device__ __forceinline__ void ln_stats(const float (&v)[32], float& mean, float& rstd) {
;     ...
;   rstd = rsqrtf(wave_sum(q) * (1.f / DM) + 1e-5f);
; template <int MODE>
; __device__ void phase_ln(const Params& p, u16* smem) {
;     ...
;     g_cv4 pg = opaque_g<g_cv4>(gam + lane * 4);
;     g_cv4 pb = opaque_g<g_cv4>(bet + lane * 4);
; #pragma unroll
;     for (int q = 0; q < 2; q++) {
;       g_v4 po = opaque_g<g_v4>(p.out + (long)(rb + q) * DM + lane * 4);
;       g_u2 ph = opaque_g<g_u2>(p.hb() + (long)(rb + q) * DM + lane * 4);
; #pragma unroll
;       for (int i = 0; i < 8; i++) {
;         f32x4 g = pg[i * 64], b = pb[i * 64];
;         f32x4 o4;
; #pragma unroll
;         for (int e = 0; e < 4; e++) o4[e] = (v[q][i * 4 + e] - mean[q]) * rstd[q] * g[e] + b[e];
;         if (MODE == 2) po[i * 64] = o4;
;         else { u32x2 w = {pack2(o4[0], o4[1]), pack2(o4[2], o4[3])}; ph[i * 64] = w; }
;       }
	v_lshlrev_b32_e32 v154, 16, v42
	v_cndmask_b32_e32 v82, v82, v83, vcc
	v_rsq_f32_e32 v82, v82
	v_and_b32_e32 v155, 0xffff0000, v42
	v_pk_fma_f32 v[50:51], v[146:147], s[2:3], v[50:51] op_sel_hi:[1,0,1]
	v_lshlrev_b32_e32 v42, 16, v43
	v_mul_f32_e32 v83, 0x45800000, v82
	v_cndmask_b32_e32 v82, v82, v83, vcc
	v_pk_mul_f32 v[114:115], v[124:125], v[82:83] op_sel_hi:[1,0]
	v_pk_mul_f32 v[116:117], v[126:127], v[82:83] op_sel_hi:[1,0]
	s_waitcnt vmcnt(0)
	v_pk_fma_f32 v[0:1], v[0:1], v[114:115], v[4:5]
	v_pk_fma_f32 v[2:3], v[2:3], v[116:117], v[6:7]
	global_store_dwordx4 v[58:59], v[0:3], off nt
	global_load_dwordx4 v[0:3], v[20:21], off offset:1024
	s_nop 0
	global_load_dwordx4 v[4:7], v[22:23], off offset:1024
	v_pk_mul_f32 v[114:115], v[130:131], v[82:83] op_sel_hi:[1,0]
	v_pk_mul_f32 v[116:117], v[128:129], v[82:83] op_sel_hi:[1,0]
	v_lshlrev_b32_e32 v130, 16, v66
	v_and_b32_e32 v131, 0xffff0000, v66
	v_pk_mul_f32 v[66:67], v[96:97], v[82:83] op_sel_hi:[1,0]
	v_and_b32_e32 v124, 0xffff0000, v80
	v_lshlrev_b32_e32 v125, 16, v80
	v_and_b32_e32 v126, 0xffff0000, v79
	v_lshlrev_b32_e32 v127, 16, v79
	v_and_b32_e32 v128, 0xffff0000, v81
	v_lshlrev_b32_e32 v129, 16, v81
	v_pk_mul_f32 v[40:41], v[94:95], v[82:83] op_sel_hi:[1,0]
	v_pk_mul_f32 v[38:39], v[92:93], v[82:83] op_sel_hi:[1,0]
	v_lshlrev_b32_e32 v96, 16, v64
	v_and_b32_e32 v97, 0xffff0000, v64
	v_lshlrev_b32_e32 v64, 16, v65
	v_and_b32_e32 v65, 0xffff0000, v65
	v_pk_add_f32 v[92:93], v[122:123], v[124:125]
	v_and_b32_e32 v43, 0xffff0000, v43
	v_pk_add_f32 v[42:43], v[158:159], v[42:43]
	v_pk_add_f32 v[94:95], v[126:127], v[128:129]
	v_pk_fma_f32 v[42:43], v[156:157], s[2:3], v[42:43] op_sel_hi:[1,0,1]
	s_waitcnt vmcnt(0)
	v_pk_fma_f32 v[0:1], v[0:1], v[116:117], v[4:5]
	v_pk_fma_f32 v[2:3], v[2:3], v[114:115], v[6:7]
	global_store_dwordx4 v[58:59], v[0:3], off offset:1024 nt
	global_load_dwordx4 v[0:3], v[20:21], off offset:2048
	s_nop 0
	global_load_dwordx4 v[4:7], v[22:23], off offset:2048
	v_pk_mul_f32 v[114:115], v[136:137], v[82:83] op_sel_hi:[1,0]
	v_pk_mul_f32 v[116:117], v[134:135], v[82:83] op_sel_hi:[1,0]
	v_lshlrev_b32_e32 v134, 16, v68
	v_and_b32_e32 v135, 0xffff0000, v68
	v_pk_mul_f32 v[68:69], v[98:99], v[82:83] op_sel_hi:[1,0]
	v_lshlrev_b32_e32 v98, 16, v52
	v_and_b32_e32 v99, 0xffff0000, v52
	v_lshlrev_b32_e32 v136, 16, v70
	v_and_b32_e32 v137, 0xffff0000, v70
	v_pk_add_f32 v[122:123], v[134:135], v[136:137]
	v_lshlrev_b32_e32 v70, 16, v71
	v_and_b32_e32 v71, 0xffff0000, v71
	v_pk_add_f32 v[70:71], v[140:141], v[70:71]
	v_lshlrev_b32_e32 v52, 16, v53
	v_pk_fma_f32 v[70:71], v[138:139], s[2:3], v[70:71] op_sel_hi:[1,0,1]
	v_and_b32_e32 v53, 0xffff0000, v53
	s_waitcnt vmcnt(0)
	v_pk_fma_f32 v[0:1], v[0:1], v[116:117], v[4:5]
	v_pk_fma_f32 v[2:3], v[2:3], v[114:115], v[6:7]
	global_store_dwordx4 v[58:59], v[0:3], off offset:2048 nt
	global_load_dwordx4 v[114:117], v[20:21], off offset:3072
	global_load_dwordx4 v[118:121], v[22:23], off offset:3072
	v_lshlrev_b64 v[0:1], 13, v[44:45]
	v_lshl_add_u64 v[4:5], v[16:17], 0, v[0:1]
	v_add_co_u32_e32 v0, vcc, s6, v20
	v_and_b32_e32 v44, 0xffff0000, v76
	s_nop 0
	v_addc_co_u32_e32 v1, vcc, 0, v21, vcc
	v_add_co_u32_e32 v2, vcc, s6, v22
	v_lshlrev_b32_e32 v45, 16, v76
	s_nop 0
	v_addc_co_u32_e32 v3, vcc, 0, v23, vcc
	v_add_co_u32_e32 v6, vcc, s6, v58
	v_pk_fma_f32 v[44:45], v[44:45], s[2:3], v[92:93] op_sel_hi:[1,0,1]
	s_nop 0
	v_addc_co_u32_e32 v7, vcc, 0, v59, vcc
	v_and_b32_e32 v76, 0xffff0000, v77
	v_lshlrev_b32_e32 v77, 16, v77
	v_pk_fma_f32 v[76:77], v[76:77], s[2:3], v[94:95] op_sel_hi:[1,0,1]
	s_waitcnt vmcnt(0)
	v_pk_fma_f32 v[66:67], v[114:115], v[66:67], v[118:119]
	v_pk_fma_f32 v[68:69], v[116:117], v[68:69], v[120:121]
	global_store_dwordx4 v[58:59], v[66:69], off offset:3072 nt
	global_load_dwordx4 v[66:69], v[0:1], off
	s_nop 0
	global_load_dwordx4 v[78:81], v[2:3], off
	v_lshlrev_b32_e32 v118, 16, v46
	v_and_b32_e32 v119, 0xffff0000, v46
	v_lshlrev_b32_e32 v120, 16, v48
	v_and_b32_e32 v121, 0xffff0000, v48
	v_lshlrev_b32_e32 v58, 16, v62
	v_and_b32_e32 v59, 0xffff0000, v62
	v_lshlrev_b32_e32 v62, 16, v63
	v_and_b32_e32 v63, 0xffff0000, v63
	v_lshlrev_b32_e32 v114, 16, v54
	v_and_b32_e32 v115, 0xffff0000, v54
	v_lshlrev_b32_e32 v116, 16, v56
	v_and_b32_e32 v117, 0xffff0000, v56
	v_pk_add_f32 v[62:63], v[62:63], v[64:65]
	v_pk_add_f32 v[64:65], v[114:115], v[116:117]
	v_pk_fma_f32 v[60:61], v[60:61], s[2:3], v[62:63] op_sel_hi:[1,0,1]
	v_pk_fma_f32 v[62:63], v[98:99], s[2:3], v[64:65] op_sel_hi:[1,0,1]
	v_pk_add_f32 v[58:59], v[58:59], v[96:97]
	v_lshlrev_b32_e32 v54, 16, v55
	v_pk_fma_f32 v[58:59], v[142:143], s[2:3], v[58:59] op_sel_hi:[1,0,1]
	v_and_b32_e32 v55, 0xffff0000, v55
	v_lshlrev_b32_e32 v56, 16, v57
	v_and_b32_e32 v57, 0xffff0000, v57
	v_pk_add_f32 v[54:55], v[54:55], v[56:57]
	v_pk_add_f32 v[56:57], v[120:121], v[144:145]
	v_pk_fma_f32 v[52:53], v[52:53], s[2:3], v[54:55] op_sel_hi:[1,0,1]
	v_pk_fma_f32 v[54:55], v[118:119], s[2:3], v[56:57] op_sel_hi:[1,0,1]
	v_pk_add_f32 v[96:97], v[152:153], v[154:155]
	s_waitcnt vmcnt(0)
; template <class G, class T> __device__ __forceinline__ G opaque_g(T* q) { asm volatile("" : "+v"(q)); return (G)q; }
; __device__ __forceinline__ void ln_stats(const float (&v)[32], float& mean, float& rstd) {
;   float s = 0.f;
; #pragma unroll
;   for (int i = 0; i < 32; i++) s += v[i];
;   mean = wave_sum(s) * (1.f / DM);
;   float q = 0.f;
; #pragma unroll
;   for (int i = 0; i < 32; i++) { float d = v[i] - mean; q += d * d; }
;   rstd = rsqrtf(wave_sum(q) * (1.f / DM) + 1e-5f);
; }
; template <int MODE>
; __device__ void phase_ln(const Params& p, u16* smem) {
;     ...
;     g_cv4 pg = opaque_g<g_cv4>(gam + lane * 4);
;     g_cv4 pb = opaque_g<g_cv4>(bet + lane * 4);
; #pragma unroll
;     for (int q = 0; q < 2; q++) {
;       g_v4 po = opaque_g<g_v4>(p.out + (long)(rb + q) * DM + lane * 4);
;       g_u2 ph = opaque_g<g_u2>(p.hb() + (long)(rb + q) * DM + lane * 4);
; #pragma unroll
;       for (int i = 0; i < 8; i++) {
;         f32x4 g = pg[i * 64], b = pb[i * 64];
;         f32x4 o4;
; #pragma unroll
;         for (int e = 0; e < 4; e++) o4[e] = (v[q][i * 4 + e] - mean[q]) * rstd[q] * g[e] + b[e];
;         if (MODE == 2) po[i * 64] = o4;
;         else { u32x2 w = {pack2(o4[0], o4[1]), pack2(o4[2], o4[3])}; ph[i * 64] = w; }
;       }
	v_pk_fma_f32 v[38:39], v[66:67], v[38:39], v[78:79]
	v_pk_fma_f32 v[40:41], v[68:69], v[40:41], v[80:81]
	global_store_dwordx4 v[6:7], v[38:41], off nt
	global_load_dwordx4 v[38:41], v[0:1], off offset:1024
	s_nop 0
	global_load_dwordx4 v[46:49], v[2:3], off offset:1024
	v_lshlrev_b32_e32 v66, 16, v36
	v_and_b32_e32 v67, 0xffff0000, v36
	v_lshlrev_b32_e32 v78, 16, v28
	v_and_b32_e32 v79, 0xffff0000, v28
	v_lshlrev_b32_e32 v80, 16, v30
	v_and_b32_e32 v81, 0xffff0000, v30
	v_lshlrev_b32_e32 v28, 16, v29
	v_and_b32_e32 v29, 0xffff0000, v29
	v_lshlrev_b32_e32 v30, 16, v31
	v_and_b32_e32 v31, 0xffff0000, v31
	v_lshlrev_b32_e32 v68, 16, v26
	v_and_b32_e32 v69, 0xffff0000, v26
	v_lshlrev_b32_e32 v26, 16, v27
	v_and_b32_e32 v27, 0xffff0000, v27
	v_pk_add_f32 v[66:67], v[162:163], v[66:67]
	v_pk_add_f32 v[28:29], v[28:29], v[30:31]
	v_pk_fma_f32 v[64:65], v[160:161], s[2:3], v[66:67] op_sel_hi:[1,0,1]
	v_pk_fma_f32 v[66:67], v[26:27], s[2:3], v[28:29] op_sel_hi:[1,0,1]
	v_pk_mul_f32 v[28:29], v[90:91], v[82:83] op_sel_hi:[1,0]
	v_pk_mul_f32 v[26:27], v[88:89], v[82:83] op_sel_hi:[1,0]
	v_lshlrev_b32_e32 v36, 16, v37
	v_and_b32_e32 v37, 0xffff0000, v37
	v_pk_add_f32 v[34:35], v[34:35], v[36:37]
	v_pk_add_f32 v[36:37], v[78:79], v[80:81]
	v_pk_fma_f32 v[34:35], v[32:33], s[2:3], v[34:35] op_sel_hi:[1,0,1]
	v_pk_fma_f32 v[78:79], v[130:131], s[2:3], v[122:123] op_sel_hi:[1,0,1]
	v_pk_fma_f32 v[36:37], v[68:69], s[2:3], v[36:37] op_sel_hi:[1,0,1]
	v_add_f32_e32 v68, 0, v78
	v_pk_fma_f32 v[56:57], v[150:151], s[2:3], v[96:97] op_sel_hi:[1,0,1]
	s_waitcnt vmcnt(0)
	v_pk_fma_f32 v[26:27], v[38:39], v[26:27], v[46:47]
	v_pk_fma_f32 v[28:29], v[40:41], v[28:29], v[48:49]
	global_store_dwordx4 v[6:7], v[26:29], off offset:1024 nt
	global_load_dwordx4 v[26:29], v[0:1], off offset:2048
	s_nop 0
	global_load_dwordx4 v[30:33], v[2:3], off offset:2048
	v_add_f32_e32 v38, v79, v68
	v_add_f32_e32 v38, v70, v38
	v_add_f32_e32 v38, v71, v38
	v_add_f32_e32 v38, v58, v38
	v_add_f32_e32 v38, v59, v38
	v_add_f32_e32 v38, v60, v38
	v_add_f32_e32 v38, v61, v38
	v_add_f32_e32 v38, v62, v38
	v_add_f32_e32 v38, v63, v38
	v_add_f32_e32 v38, v52, v38
	v_add_f32_e32 v38, v53, v38
	v_add_f32_e32 v38, v54, v38
	v_add_f32_e32 v38, v55, v38
	v_add_f32_e32 v38, v50, v38
	v_add_f32_e32 v38, v51, v38
	v_add_f32_e32 v38, v56, v38
	v_add_f32_e32 v38, v57, v38
	v_add_f32_e32 v38, v42, v38
	v_add_f32_e32 v38, v43, v38
	v_add_f32_e32 v38, v64, v38
	v_add_f32_e32 v38, v65, v38
	v_add_f32_e32 v38, v34, v38
	v_add_f32_e32 v38, v35, v38
	v_add_f32_e32 v38, v36, v38
	v_add_f32_e32 v38, v37, v38
	v_add_f32_e32 v38, v66, v38
	v_add_f32_e32 v38, v67, v38
	v_add_f32_e32 v38, v45, v38
	v_add_f32_e32 v38, v44, v38
	v_add_f32_e32 v38, v77, v38
	v_add_f32_e32 v38, v76, v38
	ds_bpermute_b32 v39, v113, v38
	v_pk_mul_f32 v[40:41], v[84:85], v[82:83] op_sel_hi:[1,0]
	s_waitcnt lgkmcnt(0)
	v_add_f32_e32 v38, v38, v39
	ds_bpermute_b32 v39, v112, v38
	s_waitcnt lgkmcnt(0)
	v_add_f32_e32 v38, v38, v39
	ds_bpermute_b32 v39, v111, v38
	s_waitcnt lgkmcnt(0)
	v_add_f32_e32 v38, v38, v39
	ds_bpermute_b32 v39, v110, v38
	s_waitcnt lgkmcnt(0)
	v_add_f32_e32 v46, v38, v39
	v_pk_mul_f32 v[38:39], v[86:87], v[82:83] op_sel_hi:[1,0]
	s_waitcnt vmcnt(0)
	v_pk_fma_f32 v[26:27], v[26:27], v[40:41], v[30:31]
	v_pk_fma_f32 v[28:29], v[28:29], v[38:39], v[32:33]
	global_store_dwordx4 v[6:7], v[26:29], off offset:2048 nt
	global_load_dwordx4 v[26:29], v[0:1], off offset:3072
	s_nop 0
	global_load_dwordx4 v[30:33], v[2:3], off offset:3072
	ds_bpermute_b32 v38, v109, v46
	s_waitcnt lgkmcnt(0)
	v_add_f32_e32 v38, v46, v38
	ds_bpermute_b32 v39, v19, v38
	s_waitcnt lgkmcnt(0)
	v_add_f32_e32 v38, v38, v39
	v_mul_f32_e32 v38, 0x3a000000, v38
	v_pk_add_f32 v[40:41], v[78:79], v[38:39] op_sel_hi:[1,0] neg_lo:[0,1] neg_hi:[0,1]
	v_pk_add_f32 v[46:47], v[70:71], v[38:39] op_sel_hi:[1,0] neg_lo:[0,1] neg_hi:[0,1]
	v_pk_add_f32 v[48:49], v[58:59], v[38:39] op_sel_hi:[1,0] neg_lo:[0,1] neg_hi:[0,1]
	v_pk_add_f32 v[58:59], v[60:61], v[38:39] op_sel_hi:[1,0] neg_lo:[0,1] neg_hi:[0,1]
	v_pk_add_f32 v[60:61], v[62:63], v[38:39] op_sel_hi:[1,0] neg_lo:[0,1] neg_hi:[0,1]
	v_pk_add_f32 v[62:63], v[64:65], v[38:39] op_sel_hi:[1,0] neg_lo:[0,1] neg_hi:[0,1]
	v_pk_add_f32 v[64:65], v[66:67], v[38:39] op_sel_hi:[1,0] neg_lo:[0,1] neg_hi:[0,1]
	v_pk_mul_f32 v[66:67], v[40:41], v[40:41]
	v_pk_mul_f32 v[68:69], v[46:47], v[46:47]
	v_add_f32_e32 v66, v66, v67
	v_add_f32_e32 v66, v68, v66
	v_pk_mul_f32 v[70:71], v[48:49], v[48:49]
	v_add_f32_e32 v66, v69, v66
	v_add_f32_e32 v66, v70, v66
	v_pk_add_f32 v[52:53], v[52:53], v[38:39] op_sel_hi:[1,0] neg_lo:[0,1] neg_hi:[0,1]
	v_pk_add_f32 v[54:55], v[54:55], v[38:39] op_sel_hi:[1,0] neg_lo:[0,1] neg_hi:[0,1]
	v_pk_add_f32 v[50:51], v[50:51], v[38:39] op_sel_hi:[1,0] neg_lo:[0,1] neg_hi:[0,1]
	v_pk_add_f32 v[56:57], v[56:57], v[38:39] op_sel_hi:[1,0] neg_lo:[0,1] neg_hi:[0,1]
	v_pk_add_f32 v[42:43], v[42:43], v[38:39] op_sel_hi:[1,0] neg_lo:[0,1] neg_hi:[0,1]
	v_pk_add_f32 v[34:35], v[34:35], v[38:39] op_sel_hi:[1,0] neg_lo:[0,1] neg_hi:[0,1]
	v_pk_add_f32 v[36:37], v[36:37], v[38:39] op_sel_hi:[1,0] neg_lo:[0,1] neg_hi:[0,1]
	v_pk_add_f32 v[44:45], v[44:45], v[38:39] op_sel_hi:[1,0] neg_lo:[0,1] neg_hi:[0,1]
	v_pk_add_f32 v[38:39], v[76:77], v[38:39] op_sel_hi:[1,0] neg_lo:[0,1] neg_hi:[0,1]
	v_pk_mul_f32 v[76:77], v[58:59], v[58:59]
	v_add_f32_e32 v66, v71, v66
	v_add_f32_e32 v66, v76, v66
	v_pk_mul_f32 v[78:79], v[60:61], v[60:61]
	v_add_f32_e32 v66, v77, v66
	v_add_f32_e32 v66, v78, v66
	v_pk_mul_f32 v[80:81], v[52:53], v[52:53]
	v_add_f32_e32 v66, v79, v66
	v_add_f32_e32 v66, v80, v66
	v_pk_mul_f32 v[84:85], v[54:55], v[54:55]
	v_add_f32_e32 v66, v81, v66
	v_add_f32_e32 v66, v84, v66
	v_pk_mul_f32 v[86:87], v[50:51], v[50:51]
	v_add_f32_e32 v66, v85, v66
	v_add_f32_e32 v66, v86, v66
	v_add_f32_e32 v70, v87, v66
	v_pk_mul_f32 v[66:67], v[72:73], v[82:83] op_sel_hi:[1,0]
	v_pk_mul_f32 v[68:69], v[74:75], v[82:83] op_sel_hi:[1,0]
	v_pk_mul_f32 v[88:89], v[56:57], v[56:57]
	v_pk_mul_f32 v[90:91], v[42:43], v[42:43]
	v_pk_mul_f32 v[92:93], v[62:63], v[62:63]
	v_pk_mul_f32 v[94:95], v[34:35], v[34:35]
	v_pk_mul_f32 v[96:97], v[36:37], v[36:37]
	v_pk_mul_f32 v[98:99], v[64:65], v[64:65]
	v_pk_mul_f32 v[114:115], v[44:45], v[44:45]
	v_pk_mul_f32 v[116:117], v[38:39], v[38:39]
	s_waitcnt vmcnt(0)
; template <class G, class T> __device__ __forceinline__ G opaque_g(T* q) { asm volatile("" : "+v"(q)); return (G)q; }
; __device__ __forceinline__ void ln_stats(const float (&v)[32], float& mean, float& rstd) {
;   float s = 0.f;
; #pragma unroll
;   for (int i = 0; i < 32; i++) s += v[i];
;   mean = wave_sum(s) * (1.f / DM);
;   float q = 0.f;
; #pragma unroll
;   for (int i = 0; i < 32; i++) { float d = v[i] - mean; q += d * d; }
;   rstd = rsqrtf(wave_sum(q) * (1.f / DM) + 1e-5f);
; }
; template <int MODE>
; __device__ void phase_ln(const Params& p, u16* smem) {
;     ...
; #pragma unroll
;     for (int q = 0; q < 2; q++) {
;       g_v4 po = opaque_g<g_v4>(p.out + (long)(rb + q) * DM + lane * 4);
;       g_u2 ph = opaque_g<g_u2>(p.hb() + (long)(rb + q) * DM + lane * 4);
; #pragma unroll
;       for (int i = 0; i < 8; i++) {
;         f32x4 g = pg[i * 64], b = pb[i * 64];
;         f32x4 o4;
; #pragma unroll
;         for (int e = 0; e < 4; e++) o4[e] = (v[q][i * 4 + e] - mean[q]) * rstd[q] * g[e] + b[e];
;         if (MODE == 2) po[i * 64] = o4;
;         else { u32x2 w = {pack2(o4[0], o4[1]), pack2(o4[2], o4[3])}; ph[i * 64] = w; }
;       }
	v_pk_fma_f32 v[26:27], v[26:27], v[66:67], v[30:31] op_sel:[0,1,0] op_sel_hi:[1,0,1]
	v_pk_fma_f32 v[28:29], v[28:29], v[68:69], v[32:33] op_sel:[0,1,0] op_sel_hi:[1,0,1]
	global_store_dwordx4 v[6:7], v[26:29], off offset:3072 nt
	global_load_dwordx4 v[24:27], v[20:21], off
	global_load_dwordx4 v[28:31], v[22:23], off
	v_add_f32_e32 v6, v88, v70
	v_add_f32_e32 v6, v89, v6
	v_add_f32_e32 v6, v90, v6
	v_add_f32_e32 v6, v91, v6
	v_add_f32_e32 v6, v92, v6
	v_add_f32_e32 v6, v93, v6
	v_add_f32_e32 v6, v94, v6
	v_add_f32_e32 v6, v95, v6
	v_add_f32_e32 v6, v96, v6
	v_add_f32_e32 v6, v97, v6
	v_add_f32_e32 v6, v98, v6
	v_add_f32_e32 v6, v99, v6
	v_add_f32_e32 v6, v115, v6
	v_add_f32_e32 v6, v114, v6
	v_add_f32_e32 v6, v117, v6
	v_add_f32_e32 v6, v116, v6
	ds_bpermute_b32 v7, v113, v6
	s_waitcnt lgkmcnt(0)
	v_add_f32_e32 v6, v6, v7
	ds_bpermute_b32 v7, v112, v6
	s_waitcnt lgkmcnt(0)
	v_add_f32_e32 v6, v6, v7
	ds_bpermute_b32 v7, v111, v6
	s_waitcnt lgkmcnt(0)
	v_add_f32_e32 v6, v6, v7
	ds_bpermute_b32 v7, v110, v6
	s_waitcnt lgkmcnt(0)
	v_add_f32_e32 v6, v6, v7
	ds_bpermute_b32 v7, v109, v6
	s_waitcnt lgkmcnt(0)
	v_add_f32_e32 v6, v6, v7
	ds_bpermute_b32 v7, v19, v6
	s_waitcnt lgkmcnt(0)
	v_add_f32_e32 v6, v6, v7
	v_fmamk_f32 v6, v6, 0x3a000000, v108
	v_mul_f32_e32 v7, 0x4b800000, v6
	v_cmp_gt_f32_e32 vcc, s5, v6
	s_nop 1
	v_cndmask_b32_e32 v6, v6, v7, vcc
	v_rsq_f32_e32 v6, v6
	s_nop 0
	v_mul_f32_e32 v7, 0x45800000, v6
	v_cndmask_b32_e32 v32, v6, v7, vcc
	v_pk_mul_f32 v[6:7], v[46:47], v[32:33] op_sel_hi:[1,0]
	v_pk_mul_f32 v[40:41], v[40:41], v[32:33] op_sel_hi:[1,0]
	s_waitcnt vmcnt(0)
	v_pk_fma_f32 v[26:27], v[26:27], v[6:7], v[30:31]
	v_pk_fma_f32 v[24:25], v[24:25], v[40:41], v[28:29]
	global_store_dwordx4 v[4:5], v[24:27], off nt
	global_load_dwordx4 v[24:27], v[20:21], off offset:1024
	s_nop 0
	global_load_dwordx4 v[28:31], v[22:23], off offset:1024
	v_pk_mul_f32 v[6:7], v[58:59], v[32:33] op_sel_hi:[1,0]
	v_pk_mul_f32 v[40:41], v[48:49], v[32:33] op_sel_hi:[1,0]
	s_waitcnt vmcnt(0)
	v_pk_fma_f32 v[26:27], v[26:27], v[6:7], v[30:31]
	v_pk_fma_f32 v[24:25], v[24:25], v[40:41], v[28:29]
	global_store_dwordx4 v[4:5], v[24:27], off offset:1024 nt
	global_load_dwordx4 v[24:27], v[20:21], off offset:2048
	s_nop 0
	global_load_dwordx4 v[28:31], v[22:23], off offset:2048
	v_pk_mul_f32 v[6:7], v[52:53], v[32:33] op_sel_hi:[1,0]
	v_pk_mul_f32 v[40:41], v[60:61], v[32:33] op_sel_hi:[1,0]
	s_waitcnt vmcnt(0)
	v_pk_fma_f32 v[26:27], v[26:27], v[6:7], v[30:31]
	v_pk_fma_f32 v[24:25], v[24:25], v[40:41], v[28:29]
	global_store_dwordx4 v[4:5], v[24:27], off offset:2048 nt
	global_load_dwordx4 v[24:27], v[20:21], off offset:3072
	s_nop 0
	global_load_dwordx4 v[28:31], v[22:23], off offset:3072
	v_pk_mul_f32 v[6:7], v[50:51], v[32:33] op_sel_hi:[1,0]
	v_pk_mul_f32 v[20:21], v[54:55], v[32:33] op_sel_hi:[1,0]
	s_waitcnt vmcnt(0)
	v_pk_fma_f32 v[22:23], v[26:27], v[6:7], v[30:31]
	v_pk_fma_f32 v[20:21], v[24:25], v[20:21], v[28:29]
	global_store_dwordx4 v[4:5], v[20:23], off offset:3072 nt
	global_load_dwordx4 v[20:23], v[0:1], off
	s_nop 0
	global_load_dwordx4 v[24:27], v[2:3], off
	v_pk_mul_f32 v[6:7], v[42:43], v[32:33] op_sel_hi:[1,0]
	v_pk_mul_f32 v[28:29], v[56:57], v[32:33] op_sel_hi:[1,0]
	v_add_co_u32_e32 v30, vcc, s6, v4
	s_waitcnt vmcnt(0)
	v_pk_fma_f32 v[6:7], v[6:7], v[22:23], v[26:27]
	v_addc_co_u32_e32 v31, vcc, 0, v5, vcc
	v_pk_fma_f32 v[4:5], v[28:29], v[20:21], v[24:25]
	global_store_dwordx4 v[30:31], v[4:7], off nt
	global_load_dwordx4 v[4:7], v[0:1], off offset:1024
	s_nop 0
	global_load_dwordx4 v[20:23], v[2:3], off offset:1024
	v_pk_mul_f32 v[24:25], v[34:35], v[32:33] op_sel_hi:[1,0]
	v_pk_mul_f32 v[26:27], v[62:63], v[32:33] op_sel_hi:[1,0]
	v_cmp_lt_i32_e32 vcc, s7, v132
	s_or_b64 s[0:1], vcc, s[0:1]
	s_waitcnt vmcnt(0)
	v_pk_fma_f32 v[4:5], v[26:27], v[4:5], v[20:21]
	v_pk_fma_f32 v[6:7], v[24:25], v[6:7], v[22:23]
	global_store_dwordx4 v[30:31], v[4:7], off offset:1024 nt
	global_load_dwordx4 v[4:7], v[0:1], off offset:2048
	s_nop 0
	global_load_dwordx4 v[20:23], v[2:3], off offset:2048
	v_pk_mul_f32 v[24:25], v[64:65], v[32:33] op_sel_hi:[1,0]
	v_pk_mul_f32 v[26:27], v[36:37], v[32:33] op_sel_hi:[1,0]
	s_waitcnt vmcnt(0)
	v_pk_fma_f32 v[6:7], v[24:25], v[6:7], v[22:23]
	v_pk_fma_f32 v[4:5], v[26:27], v[4:5], v[20:21]
	global_store_dwordx4 v[30:31], v[4:7], off offset:2048 nt
	global_load_dwordx4 v[4:7], v[0:1], off offset:3072
	s_nop 0
	global_load_dwordx4 v[20:23], v[2:3], off offset:3072
	v_pk_mul_f32 v[0:1], v[44:45], v[32:33] op_sel_hi:[1,0]
	v_pk_mul_f32 v[2:3], v[38:39], v[32:33] op_sel_hi:[1,0]
	s_waitcnt vmcnt(0)
	v_pk_fma_f32 v[0:1], v[0:1], v[4:5], v[20:21] op_sel:[1,0,0] op_sel_hi:[0,1,1]
	v_pk_fma_f32 v[2:3], v[2:3], v[6:7], v[22:23] op_sel:[1,0,0] op_sel_hi:[0,1,1]
	global_store_dwordx4 v[30:31], v[0:3], off offset:3072 nt
	s_andn2_b64 exec, exec, s[0:1]
	s_cbranch_execnz .LBB0_1054
